# prologue/epilogue de-serialisation: G3 SwiGLU epilogue regenerated with 8-wide batched independent ops (no dependent trans chains, no nops), bit-identical
# baseline (speedup 1.0000x reference)
; __device__ __forceinline__ unsigned cvt_pk_bf16(float lo, float hi) { unsigned r; asm volatile("v_cvt_pk_bf16_f32 %0, %1, %2" : "=v"(r) : "v"(lo), "v"(hi)); return r; }
;     __device__ __forceinline__ void operator()(const f32x4 (&acc)[2][2][4][2], const Unit& u, int wr, int wc, int fr, int fq) const {
;         const int row0 = u.pm * BM + wr * 64 + fr, col0 = u.pn * HALF + wc * 32 + 8 * fq;
; #pragma unroll
;         for (int ai = 0; ai < 2; ++ai)
; #pragma unroll
;             for (int m = 0; m < 4; ++m) { const int row = row0 + ai * HALF + m * 16;
;                 const float rs = rstd[row & 255];
;                 float h[8];
; #pragma unroll
;                 for (int n = 0; n < 2; ++n)
; #pragma unroll
;                     for (int e = 0; e < 4; ++e) { const float g = acc[ai][0][m][n][e] * rs, up = acc[ai][1][m][n][e] * rs;
;                         h[n * 4 + e] = g * up * __builtin_amdgcn_rcpf(1.f + __builtin_amdgcn_exp2f(-1.4426950408889634f * g)); }
;                 u32x4 w; w.x = cvt_pk_bf16(h[0], h[1]); w.y = cvt_pk_bf16(h[2], h[3]); w.z = cvt_pk_bf16(h[4], h[5]); w.w = cvt_pk_bf16(h[6], h[7]);
;                 *(u32x4*)(O + (size_t)row * ldc + col0) = w; }
.LBB0_371:
	ds_read_b32 v230, v142
	ds_read_b32 v231, v142 offset:64
	ds_read_b32 v232, v142 offset:128
	ds_read_b32 v233, v142 offset:192
	ds_read_b32 v234, v142 offset:512
	ds_read_b32 v235, v142 offset:576
	ds_read_b32 v236, v142 offset:640
	ds_read_b32 v237, v142 offset:704
	v_lshl_or_b32 v138, s76, 7, v143
	v_lshl_add_u32 v145, s77, 8, v140
	v_ashrrev_i32_e32 v139, 31, v138
	v_lshlrev_b64 v[238:239], 1, v[138:139]
	v_mov_b64_e32 v[240:241], s[4:5]
	v_mad_i64_i32 v[242:243], s[20:21], v145, s36, v[240:241]
	v_lshl_add_u64 v[242:243], v[242:243], 0, v[238:239]
	s_waitcnt lgkmcnt(0)
	v_mul_f32_e32 v124, v124, v230
	v_mul_f32_e32 v125, v125, v230
	v_mul_f32_e32 v126, v126, v230
	v_mul_f32_e32 v127, v127, v230
	v_mul_f32_e32 v116, v116, v230
	v_mul_f32_e32 v117, v117, v230
	v_mul_f32_e32 v118, v118, v230
	v_mul_f32_e32 v119, v119, v230
	v_mul_f32_e32 v120, v120, v230
	v_mul_f32_e32 v121, v121, v230
	v_mul_f32_e32 v122, v122, v230
	v_mul_f32_e32 v123, v123, v230
	v_mul_f32_e32 v112, v112, v230
	v_mul_f32_e32 v113, v113, v230
	v_mul_f32_e32 v114, v114, v230
	v_mul_f32_e32 v115, v115, v230
	v_mul_f32_e32 v214, 0xbfb8aa3b, v124
	v_mul_f32_e32 v215, 0xbfb8aa3b, v125
	v_mul_f32_e32 v216, 0xbfb8aa3b, v126
	v_mul_f32_e32 v217, 0xbfb8aa3b, v127
	v_mul_f32_e32 v218, 0xbfb8aa3b, v116
	v_mul_f32_e32 v219, 0xbfb8aa3b, v117
	v_mul_f32_e32 v220, 0xbfb8aa3b, v118
	v_mul_f32_e32 v221, 0xbfb8aa3b, v119
	v_exp_f32_e32 v214, v214
	v_exp_f32_e32 v215, v215
	v_exp_f32_e32 v216, v216
	v_exp_f32_e32 v217, v217
	v_exp_f32_e32 v218, v218
	v_exp_f32_e32 v219, v219
	v_exp_f32_e32 v220, v220
	v_exp_f32_e32 v221, v221
	v_mul_f32_e32 v120, v124, v120
	v_mul_f32_e32 v121, v125, v121
	v_mul_f32_e32 v122, v126, v122
	v_mul_f32_e32 v123, v127, v123
	v_mul_f32_e32 v112, v116, v112
	v_mul_f32_e32 v113, v117, v113
	v_mul_f32_e32 v114, v118, v114
	v_mul_f32_e32 v115, v119, v115
	v_add_f32_e32 v214, 1.0, v214
	v_add_f32_e32 v215, 1.0, v215
	v_add_f32_e32 v216, 1.0, v216
	v_add_f32_e32 v217, 1.0, v217
	v_add_f32_e32 v218, 1.0, v218
	v_add_f32_e32 v219, 1.0, v219
	v_add_f32_e32 v220, 1.0, v220
	v_add_f32_e32 v221, 1.0, v221
	v_rcp_f32_e32 v214, v214
	v_rcp_f32_e32 v215, v215
	v_rcp_f32_e32 v216, v216
	v_rcp_f32_e32 v217, v217
	v_rcp_f32_e32 v218, v218
	v_rcp_f32_e32 v219, v219
	v_rcp_f32_e32 v220, v220
	v_rcp_f32_e32 v221, v221
	v_mul_f32_e32 v124, v120, v214
	v_mul_f32_e32 v125, v121, v215
	v_mul_f32_e32 v126, v122, v216
	v_mul_f32_e32 v127, v123, v217
	v_mul_f32_e32 v116, v112, v218
	v_mul_f32_e32 v117, v113, v219
	v_mul_f32_e32 v118, v114, v220
	v_mul_f32_e32 v119, v115, v221
	v_cvt_pk_bf16_f32 v222, v124, v125
	v_cvt_pk_bf16_f32 v223, v126, v127
	v_cvt_pk_bf16_f32 v224, v116, v117
	v_cvt_pk_bf16_f32 v225, v118, v119
	global_store_dwordx4 v[242:243], v[222:225], off
	v_mul_f32_e32 v108, v108, v231
	v_mul_f32_e32 v109, v109, v231
	v_mul_f32_e32 v110, v110, v231
	v_mul_f32_e32 v111, v111, v231
	v_mul_f32_e32 v100, v100, v231
	v_mul_f32_e32 v101, v101, v231
	v_mul_f32_e32 v102, v102, v231
	v_mul_f32_e32 v103, v103, v231
	v_mul_f32_e32 v104, v104, v231
	v_mul_f32_e32 v105, v105, v231
	v_mul_f32_e32 v106, v106, v231
	v_mul_f32_e32 v107, v107, v231
	v_mul_f32_e32 v96, v96, v231
	v_mul_f32_e32 v97, v97, v231
	v_mul_f32_e32 v98, v98, v231
	v_mul_f32_e32 v99, v99, v231
	v_mul_f32_e32 v214, 0xbfb8aa3b, v108
	v_mul_f32_e32 v215, 0xbfb8aa3b, v109
	v_mul_f32_e32 v216, 0xbfb8aa3b, v110
	v_mul_f32_e32 v217, 0xbfb8aa3b, v111
	v_mul_f32_e32 v218, 0xbfb8aa3b, v100
	v_mul_f32_e32 v219, 0xbfb8aa3b, v101
	v_mul_f32_e32 v220, 0xbfb8aa3b, v102
	v_mul_f32_e32 v221, 0xbfb8aa3b, v103
	v_exp_f32_e32 v214, v214
	v_exp_f32_e32 v215, v215
	v_exp_f32_e32 v216, v216
	v_exp_f32_e32 v217, v217
	v_exp_f32_e32 v218, v218
	v_exp_f32_e32 v219, v219
	v_exp_f32_e32 v220, v220
	v_exp_f32_e32 v221, v221
	v_mul_f32_e32 v104, v108, v104
	v_mul_f32_e32 v105, v109, v105
	v_mul_f32_e32 v106, v110, v106
	v_mul_f32_e32 v107, v111, v107
	v_mul_f32_e32 v96, v100, v96
	v_mul_f32_e32 v97, v101, v97
	v_mul_f32_e32 v98, v102, v98
	v_mul_f32_e32 v99, v103, v99
	v_add_f32_e32 v214, 1.0, v214
	v_add_f32_e32 v215, 1.0, v215
	v_add_f32_e32 v216, 1.0, v216
	v_add_f32_e32 v217, 1.0, v217
	v_add_f32_e32 v218, 1.0, v218
	v_add_f32_e32 v219, 1.0, v219
	v_add_f32_e32 v220, 1.0, v220
	v_add_f32_e32 v221, 1.0, v221
	v_rcp_f32_e32 v214, v214
	v_rcp_f32_e32 v215, v215
	v_rcp_f32_e32 v216, v216
	v_rcp_f32_e32 v217, v217
	v_rcp_f32_e32 v218, v218
	v_rcp_f32_e32 v219, v219
	v_rcp_f32_e32 v220, v220
	v_rcp_f32_e32 v221, v221
	v_mul_f32_e32 v108, v104, v214
	v_mul_f32_e32 v109, v105, v215
	v_mul_f32_e32 v110, v106, v216
	v_mul_f32_e32 v111, v107, v217
	v_mul_f32_e32 v100, v96, v218
	v_mul_f32_e32 v101, v97, v219
	v_mul_f32_e32 v102, v98, v220
	v_mul_f32_e32 v103, v99, v221
	v_cvt_pk_bf16_f32 v226, v108, v109
	v_cvt_pk_bf16_f32 v227, v110, v111
	v_cvt_pk_bf16_f32 v228, v100, v101
	v_cvt_pk_bf16_f32 v229, v102, v103
	s_mov_b64 s[20:21], 0x2c000
	v_lshl_add_u64 v[244:245], v[242:243], 0, s[20:21]
	global_store_dwordx4 v[244:245], v[226:229], off
	v_mul_f32_e32 v92, v92, v232
	v_mul_f32_e32 v93, v93, v232
	v_mul_f32_e32 v94, v94, v232
	v_mul_f32_e32 v95, v95, v232
	v_mul_f32_e32 v84, v84, v232
	v_mul_f32_e32 v85, v85, v232
	v_mul_f32_e32 v86, v86, v232
	v_mul_f32_e32 v87, v87, v232
	v_mul_f32_e32 v88, v88, v232
	v_mul_f32_e32 v89, v89, v232
	v_mul_f32_e32 v90, v90, v232
	v_mul_f32_e32 v91, v91, v232
	v_mul_f32_e32 v80, v80, v232
	v_mul_f32_e32 v81, v81, v232
	v_mul_f32_e32 v82, v82, v232
	v_mul_f32_e32 v83, v83, v232
	v_mul_f32_e32 v214, 0xbfb8aa3b, v92
	v_mul_f32_e32 v215, 0xbfb8aa3b, v93
	v_mul_f32_e32 v216, 0xbfb8aa3b, v94
	v_mul_f32_e32 v217, 0xbfb8aa3b, v95
; __device__ __forceinline__ unsigned cvt_pk_bf16(float lo, float hi) { unsigned r; asm volatile("v_cvt_pk_bf16_f32 %0, %1, %2" : "=v"(r) : "v"(lo), "v"(hi)); return r; }
;     __device__ __forceinline__ void operator()(const f32x4 (&acc)[2][2][4][2], const Unit& u, int wr, int wc, int fr, int fq) const {
;         const int row0 = u.pm * BM + wr * 64 + fr, col0 = u.pn * HALF + wc * 32 + 8 * fq;
; #pragma unroll
;         for (int ai = 0; ai < 2; ++ai)
; #pragma unroll
;             for (int m = 0; m < 4; ++m) { const int row = row0 + ai * HALF + m * 16;
;                 const float rs = rstd[row & 255];
;                 float h[8];
; #pragma unroll
;                 for (int n = 0; n < 2; ++n)
; #pragma unroll
;                     for (int e = 0; e < 4; ++e) { const float g = acc[ai][0][m][n][e] * rs, up = acc[ai][1][m][n][e] * rs;
;                         h[n * 4 + e] = g * up * __builtin_amdgcn_rcpf(1.f + __builtin_amdgcn_exp2f(-1.4426950408889634f * g)); }
;                 u32x4 w; w.x = cvt_pk_bf16(h[0], h[1]); w.y = cvt_pk_bf16(h[2], h[3]); w.z = cvt_pk_bf16(h[4], h[5]); w.w = cvt_pk_bf16(h[6], h[7]);
;                 *(u32x4*)(O + (size_t)row * ldc + col0) = w; }
	v_mul_f32_e32 v218, 0xbfb8aa3b, v84
	v_mul_f32_e32 v219, 0xbfb8aa3b, v85
	v_mul_f32_e32 v220, 0xbfb8aa3b, v86
	v_mul_f32_e32 v221, 0xbfb8aa3b, v87
	v_exp_f32_e32 v214, v214
	v_exp_f32_e32 v215, v215
	v_exp_f32_e32 v216, v216
	v_exp_f32_e32 v217, v217
	v_exp_f32_e32 v218, v218
	v_exp_f32_e32 v219, v219
	v_exp_f32_e32 v220, v220
	v_exp_f32_e32 v221, v221
	v_mul_f32_e32 v88, v92, v88
	v_mul_f32_e32 v89, v93, v89
	v_mul_f32_e32 v90, v94, v90
	v_mul_f32_e32 v91, v95, v91
	v_mul_f32_e32 v80, v84, v80
	v_mul_f32_e32 v81, v85, v81
	v_mul_f32_e32 v82, v86, v82
	v_mul_f32_e32 v83, v87, v83
	v_add_f32_e32 v214, 1.0, v214
	v_add_f32_e32 v215, 1.0, v215
	v_add_f32_e32 v216, 1.0, v216
	v_add_f32_e32 v217, 1.0, v217
	v_add_f32_e32 v218, 1.0, v218
	v_add_f32_e32 v219, 1.0, v219
	v_add_f32_e32 v220, 1.0, v220
	v_add_f32_e32 v221, 1.0, v221
	v_rcp_f32_e32 v214, v214
	v_rcp_f32_e32 v215, v215
	v_rcp_f32_e32 v216, v216
	v_rcp_f32_e32 v217, v217
	v_rcp_f32_e32 v218, v218
	v_rcp_f32_e32 v219, v219
	v_rcp_f32_e32 v220, v220
	v_rcp_f32_e32 v221, v221
	v_mul_f32_e32 v92, v88, v214
	v_mul_f32_e32 v93, v89, v215
	v_mul_f32_e32 v94, v90, v216
	v_mul_f32_e32 v95, v91, v217
	v_mul_f32_e32 v84, v80, v218
	v_mul_f32_e32 v85, v81, v219
	v_mul_f32_e32 v86, v82, v220
	v_mul_f32_e32 v87, v83, v221
	v_cvt_pk_bf16_f32 v222, v92, v93
	v_cvt_pk_bf16_f32 v223, v94, v95
	v_cvt_pk_bf16_f32 v224, v84, v85
	v_cvt_pk_bf16_f32 v225, v86, v87
	s_mov_b64 s[20:21], 0x58000
	v_lshl_add_u64 v[244:245], v[242:243], 0, s[20:21]
	global_store_dwordx4 v[244:245], v[222:225], off
	v_mul_f32_e32 v76, v76, v233
	v_mul_f32_e32 v77, v77, v233
	v_mul_f32_e32 v78, v78, v233
	v_mul_f32_e32 v79, v79, v233
	v_mul_f32_e32 v68, v68, v233
	v_mul_f32_e32 v69, v69, v233
	v_mul_f32_e32 v70, v70, v233
	v_mul_f32_e32 v71, v71, v233
	v_mul_f32_e32 v72, v72, v233
	v_mul_f32_e32 v73, v73, v233
	v_mul_f32_e32 v74, v74, v233
	v_mul_f32_e32 v75, v75, v233
	v_mul_f32_e32 v64, v64, v233
	v_mul_f32_e32 v65, v65, v233
	v_mul_f32_e32 v66, v66, v233
	v_mul_f32_e32 v67, v67, v233
	v_mul_f32_e32 v214, 0xbfb8aa3b, v76
	v_mul_f32_e32 v215, 0xbfb8aa3b, v77
	v_mul_f32_e32 v216, 0xbfb8aa3b, v78
	v_mul_f32_e32 v217, 0xbfb8aa3b, v79
	v_mul_f32_e32 v218, 0xbfb8aa3b, v68
	v_mul_f32_e32 v219, 0xbfb8aa3b, v69
	v_mul_f32_e32 v220, 0xbfb8aa3b, v70
	v_mul_f32_e32 v221, 0xbfb8aa3b, v71
	v_exp_f32_e32 v214, v214
	v_exp_f32_e32 v215, v215
	v_exp_f32_e32 v216, v216
	v_exp_f32_e32 v217, v217
	v_exp_f32_e32 v218, v218
	v_exp_f32_e32 v219, v219
	v_exp_f32_e32 v220, v220
	v_exp_f32_e32 v221, v221
	v_mul_f32_e32 v72, v76, v72
	v_mul_f32_e32 v73, v77, v73
	v_mul_f32_e32 v74, v78, v74
	v_mul_f32_e32 v75, v79, v75
	v_mul_f32_e32 v64, v68, v64
	v_mul_f32_e32 v65, v69, v65
	v_mul_f32_e32 v66, v70, v66
	v_mul_f32_e32 v67, v71, v67
	v_add_f32_e32 v214, 1.0, v214
	v_add_f32_e32 v215, 1.0, v215
	v_add_f32_e32 v216, 1.0, v216
	v_add_f32_e32 v217, 1.0, v217
	v_add_f32_e32 v218, 1.0, v218
	v_add_f32_e32 v219, 1.0, v219
	v_add_f32_e32 v220, 1.0, v220
	v_add_f32_e32 v221, 1.0, v221
	v_rcp_f32_e32 v214, v214
	v_rcp_f32_e32 v215, v215
	v_rcp_f32_e32 v216, v216
	v_rcp_f32_e32 v217, v217
	v_rcp_f32_e32 v218, v218
	v_rcp_f32_e32 v219, v219
	v_rcp_f32_e32 v220, v220
	v_rcp_f32_e32 v221, v221
	v_mul_f32_e32 v76, v72, v214
	v_mul_f32_e32 v77, v73, v215
	v_mul_f32_e32 v78, v74, v216
	v_mul_f32_e32 v79, v75, v217
	v_mul_f32_e32 v68, v64, v218
	v_mul_f32_e32 v69, v65, v219
	v_mul_f32_e32 v70, v66, v220
	v_mul_f32_e32 v71, v67, v221
	v_cvt_pk_bf16_f32 v226, v76, v77
	v_cvt_pk_bf16_f32 v227, v78, v79
	v_cvt_pk_bf16_f32 v228, v68, v69
	v_cvt_pk_bf16_f32 v229, v70, v71
	s_mov_b64 s[20:21], 0x84000
	v_lshl_add_u64 v[244:245], v[242:243], 0, s[20:21]
	global_store_dwordx4 v[244:245], v[226:229], off
	v_mul_f32_e32 v60, v60, v234
	v_mul_f32_e32 v61, v61, v234
	v_mul_f32_e32 v62, v62, v234
	v_mul_f32_e32 v63, v63, v234
	v_mul_f32_e32 v52, v52, v234
	v_mul_f32_e32 v53, v53, v234
	v_mul_f32_e32 v54, v54, v234
	v_mul_f32_e32 v55, v55, v234
	v_mul_f32_e32 v56, v56, v234
	v_mul_f32_e32 v57, v57, v234
	v_mul_f32_e32 v58, v58, v234
	v_mul_f32_e32 v59, v59, v234
	v_mul_f32_e32 v48, v48, v234
	v_mul_f32_e32 v49, v49, v234
	v_mul_f32_e32 v50, v50, v234
	v_mul_f32_e32 v51, v51, v234
	v_mul_f32_e32 v214, 0xbfb8aa3b, v60
	v_mul_f32_e32 v215, 0xbfb8aa3b, v61
	v_mul_f32_e32 v216, 0xbfb8aa3b, v62
	v_mul_f32_e32 v217, 0xbfb8aa3b, v63
	v_mul_f32_e32 v218, 0xbfb8aa3b, v52
	v_mul_f32_e32 v219, 0xbfb8aa3b, v53
	v_mul_f32_e32 v220, 0xbfb8aa3b, v54
	v_mul_f32_e32 v221, 0xbfb8aa3b, v55
	v_exp_f32_e32 v214, v214
	v_exp_f32_e32 v215, v215
	v_exp_f32_e32 v216, v216
	v_exp_f32_e32 v217, v217
	v_exp_f32_e32 v218, v218
	v_exp_f32_e32 v219, v219
	v_exp_f32_e32 v220, v220
	v_exp_f32_e32 v221, v221
	v_mul_f32_e32 v56, v60, v56
	v_mul_f32_e32 v57, v61, v57
	v_mul_f32_e32 v58, v62, v58
	v_mul_f32_e32 v59, v63, v59
	v_mul_f32_e32 v48, v52, v48
	v_mul_f32_e32 v49, v53, v49
	v_mul_f32_e32 v50, v54, v50
	v_mul_f32_e32 v51, v55, v51
	v_add_f32_e32 v214, 1.0, v214
	v_add_f32_e32 v215, 1.0, v215
	v_add_f32_e32 v216, 1.0, v216
	v_add_f32_e32 v217, 1.0, v217
	v_add_f32_e32 v218, 1.0, v218
	v_add_f32_e32 v219, 1.0, v219
	v_add_f32_e32 v220, 1.0, v220
	v_add_f32_e32 v221, 1.0, v221
	v_rcp_f32_e32 v214, v214
	v_rcp_f32_e32 v215, v215
	v_rcp_f32_e32 v216, v216
	v_rcp_f32_e32 v217, v217
	v_rcp_f32_e32 v218, v218
	v_rcp_f32_e32 v219, v219
	v_rcp_f32_e32 v220, v220
	v_rcp_f32_e32 v221, v221
	v_mul_f32_e32 v60, v56, v214
	v_mul_f32_e32 v61, v57, v215
	v_mul_f32_e32 v62, v58, v216
	v_mul_f32_e32 v63, v59, v217
	v_mul_f32_e32 v52, v48, v218
	v_mul_f32_e32 v53, v49, v219
	v_mul_f32_e32 v54, v50, v220
	v_mul_f32_e32 v55, v51, v221
; __device__ __forceinline__ unsigned cvt_pk_bf16(float lo, float hi) { unsigned r; asm volatile("v_cvt_pk_bf16_f32 %0, %1, %2" : "=v"(r) : "v"(lo), "v"(hi)); return r; }
;     __device__ __forceinline__ void operator()(const f32x4 (&acc)[2][2][4][2], const Unit& u, int wr, int wc, int fr, int fq) const {
;         const int row0 = u.pm * BM + wr * 64 + fr, col0 = u.pn * HALF + wc * 32 + 8 * fq;
; #pragma unroll
;         for (int ai = 0; ai < 2; ++ai)
; #pragma unroll
;             for (int m = 0; m < 4; ++m) { const int row = row0 + ai * HALF + m * 16;
;                 const float rs = rstd[row & 255];
;                 float h[8];
; #pragma unroll
;                 for (int n = 0; n < 2; ++n)
; #pragma unroll
;                     for (int e = 0; e < 4; ++e) { const float g = acc[ai][0][m][n][e] * rs, up = acc[ai][1][m][n][e] * rs;
;                         h[n * 4 + e] = g * up * __builtin_amdgcn_rcpf(1.f + __builtin_amdgcn_exp2f(-1.4426950408889634f * g)); }
;                 u32x4 w; w.x = cvt_pk_bf16(h[0], h[1]); w.y = cvt_pk_bf16(h[2], h[3]); w.z = cvt_pk_bf16(h[4], h[5]); w.w = cvt_pk_bf16(h[6], h[7]);
;                 *(u32x4*)(O + (size_t)row * ldc + col0) = w; }
	v_cvt_pk_bf16_f32 v222, v60, v61
	v_cvt_pk_bf16_f32 v223, v62, v63
	v_cvt_pk_bf16_f32 v224, v52, v53
	v_cvt_pk_bf16_f32 v225, v54, v55
	s_mov_b64 s[20:21], 0x160000
	v_lshl_add_u64 v[244:245], v[242:243], 0, s[20:21]
	global_store_dwordx4 v[244:245], v[222:225], off
	v_mul_f32_e32 v44, v44, v235
	v_mul_f32_e32 v45, v45, v235
	v_mul_f32_e32 v46, v46, v235
	v_mul_f32_e32 v47, v47, v235
	v_mul_f32_e32 v36, v36, v235
	v_mul_f32_e32 v37, v37, v235
	v_mul_f32_e32 v38, v38, v235
	v_mul_f32_e32 v39, v39, v235
	v_mul_f32_e32 v40, v40, v235
	v_mul_f32_e32 v41, v41, v235
	v_mul_f32_e32 v42, v42, v235
	v_mul_f32_e32 v43, v43, v235
	v_mul_f32_e32 v32, v32, v235
	v_mul_f32_e32 v33, v33, v235
	v_mul_f32_e32 v34, v34, v235
	v_mul_f32_e32 v35, v35, v235
	v_mul_f32_e32 v214, 0xbfb8aa3b, v44
	v_mul_f32_e32 v215, 0xbfb8aa3b, v45
	v_mul_f32_e32 v216, 0xbfb8aa3b, v46
	v_mul_f32_e32 v217, 0xbfb8aa3b, v47
	v_mul_f32_e32 v218, 0xbfb8aa3b, v36
	v_mul_f32_e32 v219, 0xbfb8aa3b, v37
	v_mul_f32_e32 v220, 0xbfb8aa3b, v38
	v_mul_f32_e32 v221, 0xbfb8aa3b, v39
	v_exp_f32_e32 v214, v214
	v_exp_f32_e32 v215, v215
	v_exp_f32_e32 v216, v216
	v_exp_f32_e32 v217, v217
	v_exp_f32_e32 v218, v218
	v_exp_f32_e32 v219, v219
	v_exp_f32_e32 v220, v220
	v_exp_f32_e32 v221, v221
	v_mul_f32_e32 v40, v44, v40
	v_mul_f32_e32 v41, v45, v41
	v_mul_f32_e32 v42, v46, v42
	v_mul_f32_e32 v43, v47, v43
	v_mul_f32_e32 v32, v36, v32
	v_mul_f32_e32 v33, v37, v33
	v_mul_f32_e32 v34, v38, v34
	v_mul_f32_e32 v35, v39, v35
	v_add_f32_e32 v214, 1.0, v214
	v_add_f32_e32 v215, 1.0, v215
	v_add_f32_e32 v216, 1.0, v216
	v_add_f32_e32 v217, 1.0, v217
	v_add_f32_e32 v218, 1.0, v218
	v_add_f32_e32 v219, 1.0, v219
	v_add_f32_e32 v220, 1.0, v220
	v_add_f32_e32 v221, 1.0, v221
	v_rcp_f32_e32 v214, v214
	v_rcp_f32_e32 v215, v215
	v_rcp_f32_e32 v216, v216
	v_rcp_f32_e32 v217, v217
	v_rcp_f32_e32 v218, v218
	v_rcp_f32_e32 v219, v219
	v_rcp_f32_e32 v220, v220
	v_rcp_f32_e32 v221, v221
	v_mul_f32_e32 v44, v40, v214
	v_mul_f32_e32 v45, v41, v215
	v_mul_f32_e32 v46, v42, v216
	v_mul_f32_e32 v47, v43, v217
	v_mul_f32_e32 v36, v32, v218
	v_mul_f32_e32 v37, v33, v219
	v_mul_f32_e32 v38, v34, v220
	v_mul_f32_e32 v39, v35, v221
	v_cvt_pk_bf16_f32 v226, v44, v45
	v_cvt_pk_bf16_f32 v227, v46, v47
	v_cvt_pk_bf16_f32 v228, v36, v37
	v_cvt_pk_bf16_f32 v229, v38, v39
	s_mov_b64 s[20:21], 0x18c000
	v_lshl_add_u64 v[244:245], v[242:243], 0, s[20:21]
	global_store_dwordx4 v[244:245], v[226:229], off
	v_mul_f32_e32 v28, v28, v236
	v_mul_f32_e32 v29, v29, v236
	v_mul_f32_e32 v30, v30, v236
	v_mul_f32_e32 v31, v31, v236
	v_mul_f32_e32 v20, v20, v236
	v_mul_f32_e32 v21, v21, v236
	v_mul_f32_e32 v22, v22, v236
	v_mul_f32_e32 v23, v23, v236
	v_mul_f32_e32 v24, v24, v236
	v_mul_f32_e32 v25, v25, v236
	v_mul_f32_e32 v26, v26, v236
	v_mul_f32_e32 v27, v27, v236
	v_mul_f32_e32 v16, v16, v236
	v_mul_f32_e32 v17, v17, v236
	v_mul_f32_e32 v18, v18, v236
	v_mul_f32_e32 v19, v19, v236
	v_mul_f32_e32 v214, 0xbfb8aa3b, v28
	v_mul_f32_e32 v215, 0xbfb8aa3b, v29
	v_mul_f32_e32 v216, 0xbfb8aa3b, v30
	v_mul_f32_e32 v217, 0xbfb8aa3b, v31
	v_mul_f32_e32 v218, 0xbfb8aa3b, v20
	v_mul_f32_e32 v219, 0xbfb8aa3b, v21
	v_mul_f32_e32 v220, 0xbfb8aa3b, v22
	v_mul_f32_e32 v221, 0xbfb8aa3b, v23
	v_exp_f32_e32 v214, v214
	v_exp_f32_e32 v215, v215
	v_exp_f32_e32 v216, v216
	v_exp_f32_e32 v217, v217
	v_exp_f32_e32 v218, v218
	v_exp_f32_e32 v219, v219
	v_exp_f32_e32 v220, v220
	v_exp_f32_e32 v221, v221
	v_mul_f32_e32 v24, v28, v24
	v_mul_f32_e32 v25, v29, v25
	v_mul_f32_e32 v26, v30, v26
	v_mul_f32_e32 v27, v31, v27
	v_mul_f32_e32 v16, v20, v16
	v_mul_f32_e32 v17, v21, v17
	v_mul_f32_e32 v18, v22, v18
	v_mul_f32_e32 v19, v23, v19
	v_add_f32_e32 v214, 1.0, v214
	v_add_f32_e32 v215, 1.0, v215
	v_add_f32_e32 v216, 1.0, v216
	v_add_f32_e32 v217, 1.0, v217
	v_add_f32_e32 v218, 1.0, v218
	v_add_f32_e32 v219, 1.0, v219
	v_add_f32_e32 v220, 1.0, v220
	v_add_f32_e32 v221, 1.0, v221
	v_rcp_f32_e32 v214, v214
	v_rcp_f32_e32 v215, v215
	v_rcp_f32_e32 v216, v216
	v_rcp_f32_e32 v217, v217
	v_rcp_f32_e32 v218, v218
	v_rcp_f32_e32 v219, v219
	v_rcp_f32_e32 v220, v220
	v_rcp_f32_e32 v221, v221
	v_mul_f32_e32 v28, v24, v214
	v_mul_f32_e32 v29, v25, v215
	v_mul_f32_e32 v30, v26, v216
	v_mul_f32_e32 v31, v27, v217
	v_mul_f32_e32 v20, v16, v218
	v_mul_f32_e32 v21, v17, v219
	v_mul_f32_e32 v22, v18, v220
	v_mul_f32_e32 v23, v19, v221
	v_cvt_pk_bf16_f32 v222, v28, v29
	v_cvt_pk_bf16_f32 v223, v30, v31
	v_cvt_pk_bf16_f32 v224, v20, v21
	v_cvt_pk_bf16_f32 v225, v22, v23
	s_mov_b64 s[20:21], 0x1b8000
	v_lshl_add_u64 v[244:245], v[242:243], 0, s[20:21]
	global_store_dwordx4 v[244:245], v[222:225], off
	v_mul_f32_e32 v12, v12, v237
	v_mul_f32_e32 v13, v13, v237
	v_mul_f32_e32 v14, v14, v237
	v_mul_f32_e32 v15, v15, v237
	v_mul_f32_e32 v4, v4, v237
	v_mul_f32_e32 v5, v5, v237
	v_mul_f32_e32 v6, v6, v237
	v_mul_f32_e32 v7, v7, v237
	v_mul_f32_e32 v8, v8, v237
	v_mul_f32_e32 v9, v9, v237
	v_mul_f32_e32 v10, v10, v237
	v_mul_f32_e32 v11, v11, v237
	v_mul_f32_e32 v0, v0, v237
	v_mul_f32_e32 v1, v1, v237
	v_mul_f32_e32 v2, v2, v237
	v_mul_f32_e32 v3, v3, v237
	v_mul_f32_e32 v214, 0xbfb8aa3b, v12
	v_mul_f32_e32 v215, 0xbfb8aa3b, v13
	v_mul_f32_e32 v216, 0xbfb8aa3b, v14
	v_mul_f32_e32 v217, 0xbfb8aa3b, v15
	v_mul_f32_e32 v218, 0xbfb8aa3b, v4
	v_mul_f32_e32 v219, 0xbfb8aa3b, v5
	v_mul_f32_e32 v220, 0xbfb8aa3b, v6
	v_mul_f32_e32 v221, 0xbfb8aa3b, v7
	v_exp_f32_e32 v214, v214
	v_exp_f32_e32 v215, v215
	v_exp_f32_e32 v216, v216
	v_exp_f32_e32 v217, v217
	v_exp_f32_e32 v218, v218
	v_exp_f32_e32 v219, v219
	v_exp_f32_e32 v220, v220
	v_exp_f32_e32 v221, v221
	v_mul_f32_e32 v8, v12, v8
	v_mul_f32_e32 v9, v13, v9
	v_mul_f32_e32 v10, v14, v10
	v_mul_f32_e32 v11, v15, v11
	v_mul_f32_e32 v0, v4, v0
	v_mul_f32_e32 v1, v5, v1
	v_mul_f32_e32 v2, v6, v2
	v_mul_f32_e32 v3, v7, v3
	v_add_f32_e32 v214, 1.0, v214
	v_add_f32_e32 v215, 1.0, v215
	v_add_f32_e32 v216, 1.0, v216
	v_add_f32_e32 v217, 1.0, v217
	v_add_f32_e32 v218, 1.0, v218
	v_add_f32_e32 v219, 1.0, v219
	v_add_f32_e32 v220, 1.0, v220
	v_add_f32_e32 v221, 1.0, v221
	v_rcp_f32_e32 v214, v214
	v_rcp_f32_e32 v215, v215
	v_rcp_f32_e32 v216, v216
	v_rcp_f32_e32 v217, v217
	v_rcp_f32_e32 v218, v218
	v_rcp_f32_e32 v219, v219
	v_rcp_f32_e32 v220, v220
	v_rcp_f32_e32 v221, v221
	v_mul_f32_e32 v12, v8, v214
	v_mul_f32_e32 v13, v9, v215
	v_mul_f32_e32 v14, v10, v216
	v_mul_f32_e32 v15, v11, v217
	v_mul_f32_e32 v4, v0, v218
	v_mul_f32_e32 v5, v1, v219
	v_mul_f32_e32 v6, v2, v220
	v_mul_f32_e32 v7, v3, v221
	v_cvt_pk_bf16_f32 v226, v12, v13
	v_cvt_pk_bf16_f32 v227, v14, v15
	v_cvt_pk_bf16_f32 v228, v4, v5
	v_cvt_pk_bf16_f32 v229, v6, v7
	s_mov_b64 s[20:21], 0x1e4000
	v_lshl_add_u64 v[244:245], v[242:243], 0, s[20:21]
	global_store_dwordx4 v[244:245], v[226:229], off
	s_mov_b64 s[20:21], -1
	s_andn2_b64 vcc, exec, s[42:43]
	s_cbranch_vccnz .LBB0_364
	s_andn2_b64 vcc, exec, s[44:45]
	s_cbranch_vccnz .LBB0_363
	s_barrier
	s_branch .LBB0_363
